# static s_setprio 1 for waves 4-7 inside the token-mixer items (reset to 0 at item end)
# baseline (speedup 1.0000x reference)
; __device__ __forceinline__ KArgsPtr kargs() { KArgsPtr p = (KArgsPtr)__builtin_amdgcn_kernarg_segment_ptr(); asm volatile("" : "+s"(p)); return p; }
; __global__ void __launch_bounds__(512, 2) mega_fwd(Args args) {
;     ...
;                     for (int item = bx; item < 200; item += G) {
;                         KArgsPtr KA = kargs();
;                         if (item < 40) {
;                             const int vloc = item >> 3, hd = (item & 7) >> 1, dir = item & 1;
;     ...
;                             ret_item(lds, PROJ, dir ? YBK : YF, sub * 5 + vloc, vloc, hd, dir);
;     ...
;                         } else if (item < 120) {
;                             const int q = item - 40, vloc = q >> 4, hh = (q & 15) >> 1, dir = q & 1;
;     ...
;                             ssd_item(lds, PROJ, CXB, dir ? YBK : YF, KA->in[16] + l * 16, KA->in[17] + l * 16, KA->in[18] + l * 8,
;                                      sub * 5 + vloc, vloc, hh, dir);
;     ...
;                         } else {
;                             const int q = item - 120, vloc = q >> 4, nb = (q & 15) >> 1, dir = q & 1;
;     ...
;                             lru_item(lds, PROJ, dir ? YBK : YF, KA->in[7] + (size_t)l * 4 * 512, KA->in[8] + l * 512, KA->in[9] + (size_t)l * 2 * 8 * 64 * 64, KA->in[10] + l * 1024,
;                                      KA->in[11] + (size_t)l * 2 * 8 * 64 * 64, KA->in[12] + l * 1024, KA->in[13] + l * 1024, sub * 5 + vloc, vloc, nb, dir);
;     ...
;                         }
;                     }
.LBB0_428:
	s_setprio 0
	v_readlane_b32 s0, v251, 1
	s_add_i32 s8, s8, s0
	s_cmpk_gt_i32 s8, 0xc7
	v_readlane_b32 s1, v251, 2
	s_cbranch_scc1 .LBB0_672
.LBB0_429:
	v_readfirstlane_b32 s98, v170
	s_nop 3
	s_lshr_b32 s98, s98, 6
	s_cmp_ge_u32 s98, 4
	s_cbranch_scc0 .Lmix_prio_done
	s_setprio 1

; __global__ void __launch_bounds__(512, 2) mega_fwd(Args args) {
	.amdhsa_kernel _Z8mega_fwd4Args
		.amdhsa_group_segment_fixed_size 0
		.amdhsa_private_segment_fixed_size 0
		.amdhsa_kernarg_size 480
		.amdhsa_user_sgpr_count 2
		.amdhsa_user_sgpr_dispatch_ptr 0
		.amdhsa_user_sgpr_queue_ptr 0
		.amdhsa_user_sgpr_kernarg_segment_ptr 1
		.amdhsa_user_sgpr_dispatch_id 0
		.amdhsa_user_sgpr_kernarg_preload_length 0
		.amdhsa_user_sgpr_kernarg_preload_offset 0
		.amdhsa_user_sgpr_private_segment_size 0
		.amdhsa_uses_dynamic_stack 0
		.amdhsa_enable_private_segment 0
		.amdhsa_system_sgpr_workgroup_id_x 1
		.amdhsa_system_sgpr_workgroup_id_y 0
		.amdhsa_system_sgpr_workgroup_id_z 0
		.amdhsa_system_sgpr_workgroup_info 0
		.amdhsa_system_vgpr_workitem_id 2
		.amdhsa_next_free_vgpr 256
		.amdhsa_next_free_sgpr 99
		.amdhsa_accum_offset 256
		.amdhsa_reserve_vcc 1
		.amdhsa_float_round_mode_32 0
		.amdhsa_float_round_mode_16_64 0
		.amdhsa_float_denorm_mode_32 3
		.amdhsa_float_denorm_mode_16_64 3
		.amdhsa_dx10_clamp 1
		.amdhsa_ieee_mode 1
		.amdhsa_fp16_overflow 0
		.amdhsa_tg_split 0
		.amdhsa_exception_fp_ieee_invalid_op 0
		.amdhsa_exception_fp_denorm_src 0
		.amdhsa_exception_fp_ieee_div_zero 0
		.amdhsa_exception_fp_ieee_overflow 0
		.amdhsa_exception_fp_ieee_underflow 0
		.amdhsa_exception_fp_ieee_inexact 0
		.amdhsa_exception_int_div_zero 0
	.end_amdhsa_kernel

; __global__ void __launch_bounds__(512, 2) mega_fwd(Args args) {
amdhsa.kernels:
  - .agpr_count:     0
    .args:
      - .offset:         0
        .size:           224
        .value_kind:     by_value
      - .offset:         224
        .size:           4
        .value_kind:     hidden_block_count_x
      - .offset:         228
        .size:           4
        .value_kind:     hidden_block_count_y
      - .offset:         232
        .size:           4
        .value_kind:     hidden_block_count_z
      - .offset:         236
        .size:           2
        .value_kind:     hidden_group_size_x
      - .offset:         238
        .size:           2
        .value_kind:     hidden_group_size_y
      - .offset:         240
        .size:           2
        .value_kind:     hidden_group_size_z
      - .offset:         242
        .size:           2
        .value_kind:     hidden_remainder_x
      - .offset:         244
        .size:           2
        .value_kind:     hidden_remainder_y
      - .offset:         246
        .size:           2
        .value_kind:     hidden_remainder_z
      - .offset:         264
        .size:           8
        .value_kind:     hidden_global_offset_x
      - .offset:         272
        .size:           8
        .value_kind:     hidden_global_offset_y
      - .offset:         280
        .size:           8
        .value_kind:     hidden_global_offset_z
      - .offset:         288
        .size:           2
        .value_kind:     hidden_grid_dims
      - .offset:         312
        .size:           8
        .value_kind:     hidden_multigrid_sync_arg
      - .offset:         344
        .size:           4
        .value_kind:     hidden_dynamic_lds_size
    .group_segment_fixed_size: 0
    .kernarg_segment_align: 8
    .kernarg_segment_size: 480
    .language:       OpenCL C
    .language_version:
      - 2
      - 0
    .max_flat_workgroup_size: 512
    .name:           _Z8mega_fwd4Args
    .private_segment_fixed_size: 0
    .sgpr_count:     105
    .sgpr_spill_count: 309
    .symbol:         _Z8mega_fwd4Args.kd
    .uniform_work_group_size: 1
    .uses_dynamic_stack: false
    .vgpr_count:     256
    .vgpr_spill_count: 0
    .wavefront_size: 64
